# grid barrier: non-leader workgroups poll the cross-XCD generation word directly (one hop less on the release path)
# speedup vs baseline: 1.0079x; 1.0013x over previous
; __device__ __forceinline__ unsigned xb_ld(unsigned* p)              { return __hip_atomic_load(p, __ATOMIC_RELAXED, __HIP_MEMORY_SCOPE_AGENT); }
; __device__ __forceinline__ unsigned xb_add(unsigned* p, unsigned v) { return __hip_atomic_fetch_add(p, v, __ATOMIC_RELAXED, __HIP_MEMORY_SCOPE_AGENT); }
; #define XB_SPIN(cond, bar) do { unsigned _sp = 0; while (cond) { __builtin_amdgcn_s_sleep(1); \
;     if ((++_sp & 255u) == 0u) { if (xb_ld(&(bar)[XB_TMO])) break; if (_sp > XB_SPIN_CAP) { atomicAdd(&(bar)[XB_TMO], 1u); break; } } } } while (0)
; __device__ __forceinline__ void xcd_barrier(const XcdBarrier& b) {
;     ...
;         unsigned nloc = b.st[0], nx = b.st[1];
;         if (nloc == 0u) { xcd_barrier_complete(bar, b.x, nloc, nx); b.st[0] = nloc; b.st[1] = nx; }
;         const unsigned old = xb_add(&bar[XB_XSUB(b.x)], 1u);
;         const unsigned gen = old / nloc;
;         if (old + 1u == (gen + 1u) * nloc) {
;             __builtin_amdgcn_fence(__ATOMIC_RELEASE, "agent");
;             asm volatile("s_waitcnt vmcnt(0)" ::: "memory");
;             const unsigned og = xb_add(&bar[XB_TOP], 1u);
;             const unsigned tg = og / nx;
;             if (og + 1u == (tg + 1u) * nx) xb_add(&bar[XB_TOPGEN], 1u);
;             else XB_SPIN(xb_ld(&bar[XB_TOPGEN]) == tg, bar);
;             __builtin_amdgcn_fence(__ATOMIC_ACQUIRE, "agent");
;             xb_add(&bar[XB_XGEN(b.x)], 1u);
;             asm volatile("s_waitcnt vmcnt(0)" ::: "memory");
;         } else {
;             XB_SPIN(xb_ld(&bar[XB_XGEN(b.x)]) == gen, bar);
.LBB0_104:
	s_lshl_b32 s4, s58, 8
	v_readlane_b32 s6, v254, 5
	v_readlane_b32 s7, v254, 6
	s_add_u32 s4, s6, s4
	s_addc_u32 s5, s7, 0
	v_mov_b32_e32 v2, 0x1000
	v_mov_b32_e32 v4, 1
	global_atomic_add v4, v2, v4, s[4:5] offset:1024 sc0
	v_cvt_f32_u32_e32 v2, v3
	v_sub_u32_e32 v5, 0, v3
	v_rcp_iflag_f32_e32 v2, v2
	s_nop 0
	v_mul_f32_e32 v2, 0x4f7ffffe, v2
	v_cvt_u32_f32_e32 v2, v2
	v_mul_lo_u32 v5, v5, v2
	v_mul_hi_u32 v5, v2, v5
	v_add_u32_e32 v2, v2, v5
	s_waitcnt vmcnt(0)
	v_mul_hi_u32 v2, v4, v2
	v_mul_lo_u32 v5, v2, v3
	v_sub_u32_e32 v5, v4, v5
	v_add_u32_e32 v6, 1, v2
	v_cmp_ge_u32_e32 vcc, v5, v3
	v_add_u32_e32 v4, 1, v4
	s_nop 0
	v_cndmask_b32_e32 v2, v2, v6, vcc
	v_sub_u32_e32 v6, v5, v3
	v_cndmask_b32_e32 v5, v5, v6, vcc
	v_add_u32_e32 v6, 1, v2
	v_cmp_ge_u32_e32 vcc, v5, v3
	s_nop 1
	v_cndmask_b32_e32 v2, v2, v6, vcc
	v_mul_lo_u32 v5, v3, v2
	v_add_u32_e32 v3, v5, v3
	v_cmp_ne_u32_e32 vcc, v4, v3
	s_and_saveexec_b64 s[6:7], vcc
	s_xor_b64 s[6:7], exec, s[6:7]
	s_cbranch_execz .LBB0_118
	s_waitcnt lgkmcnt(0)
	s_add_u32 s12, s78, 0x83500
	s_addc_u32 s13, s79, 0
	v_mov_b32_e32 v1, 0
	global_load_dword v1, v1, s[12:13] sc1
	s_waitcnt vmcnt(0)
	v_cmp_gt_u32_e32 vcc, 1, v1
	s_and_saveexec_b64 s[8:9], vcc
	s_cbranch_execz .LBB0_117
	s_add_u32 s10, s78, 0x80200
	s_addc_u32 s11, s79, 0
	s_mov_b32 s24, 1
	s_mov_b64 s[14:15], 0
	v_mov_b32_e32 v1, 0
	s_branch .LBB0_108

; __device__ __forceinline__ unsigned xb_ld(unsigned* p)              { return __hip_atomic_load(p, __ATOMIC_RELAXED, __HIP_MEMORY_SCOPE_AGENT); }
; #define XB_SPIN(cond, bar) do { unsigned _sp = 0; while (cond) { __builtin_amdgcn_s_sleep(1); \
;     if ((++_sp & 255u) == 0u) { if (xb_ld(&(bar)[XB_TMO])) break; if (_sp > XB_SPIN_CAP) { atomicAdd(&(bar)[XB_TMO], 1u); break; } } } } while (0)
; __device__ __forceinline__ void xcd_barrier(const XcdBarrier& b) {
;     ...
;             XB_SPIN(xb_ld(&bar[XB_XGEN(b.x)]) == gen, bar);
.LBB0_112:
	global_load_dword v3, v1, s[12:13] sc1
	s_add_i32 s24, s24, 1
	s_mov_b64 s[20:21], -1
	s_waitcnt vmcnt(0)
	v_cmp_le_u32_e32 vcc, 1, v3
	s_orn2_b64 s[18:19], vcc, exec
	s_branch .LBB0_107

; __device__ __forceinline__ unsigned xb_ld(unsigned* p)              { return __hip_atomic_load(p, __ATOMIC_RELAXED, __HIP_MEMORY_SCOPE_AGENT); }
; __device__ __forceinline__ unsigned xb_add(unsigned* p, unsigned v) { return __hip_atomic_fetch_add(p, v, __ATOMIC_RELAXED, __HIP_MEMORY_SCOPE_AGENT); }
; #define XB_SPIN(cond, bar) do { unsigned _sp = 0; while (cond) { __builtin_amdgcn_s_sleep(1); \
;     if ((++_sp & 255u) == 0u) { if (xb_ld(&(bar)[XB_TMO])) break; if (_sp > XB_SPIN_CAP) { atomicAdd(&(bar)[XB_TMO], 1u); break; } } } } while (0)
; __device__ __forceinline__ void xcd_barrier(const XcdBarrier& b) {
;     ...
;         unsigned nloc = b.st[0], nx = b.st[1];
;         if (nloc == 0u) { xcd_barrier_complete(bar, b.x, nloc, nx); b.st[0] = nloc; b.st[1] = nx; }
;         const unsigned old = xb_add(&bar[XB_XSUB(b.x)], 1u);
;         const unsigned gen = old / nloc;
;         if (old + 1u == (gen + 1u) * nloc) {
;             __builtin_amdgcn_fence(__ATOMIC_RELEASE, "agent");
;             asm volatile("s_waitcnt vmcnt(0)" ::: "memory");
;             const unsigned og = xb_add(&bar[XB_TOP], 1u);
;             const unsigned tg = og / nx;
;             if (og + 1u == (tg + 1u) * nx) xb_add(&bar[XB_TOPGEN], 1u);
;             else XB_SPIN(xb_ld(&bar[XB_TOPGEN]) == tg, bar);
;             __builtin_amdgcn_fence(__ATOMIC_ACQUIRE, "agent");
;             xb_add(&bar[XB_XGEN(b.x)], 1u);
;             asm volatile("s_waitcnt vmcnt(0)" ::: "memory");
;         } else {
;             XB_SPIN(xb_ld(&bar[XB_XGEN(b.x)]) == gen, bar);
.LBB0_165:
	s_lshl_b32 s4, s58, 8
	v_readlane_b32 s6, v254, 5
	v_readlane_b32 s7, v254, 6
	s_add_u32 s4, s6, s4
	s_addc_u32 s5, s7, 0
	v_mov_b32_e32 v2, 0x1000
	v_mov_b32_e32 v4, 1
	global_atomic_add v4, v2, v4, s[4:5] offset:1024 sc0
	v_cvt_f32_u32_e32 v2, v3
	v_sub_u32_e32 v5, 0, v3
	v_rcp_iflag_f32_e32 v2, v2
	s_nop 0
	v_mul_f32_e32 v2, 0x4f7ffffe, v2
	v_cvt_u32_f32_e32 v2, v2
	v_mul_lo_u32 v5, v5, v2
	v_mul_hi_u32 v5, v2, v5
	v_add_u32_e32 v2, v2, v5
	s_waitcnt vmcnt(0)
	v_mul_hi_u32 v2, v4, v2
	v_mul_lo_u32 v5, v2, v3
	v_sub_u32_e32 v5, v4, v5
	v_add_u32_e32 v6, 1, v2
	v_cmp_ge_u32_e32 vcc, v5, v3
	v_add_u32_e32 v4, 1, v4
	s_nop 0
	v_cndmask_b32_e32 v2, v2, v6, vcc
	v_sub_u32_e32 v6, v5, v3
	v_cndmask_b32_e32 v5, v5, v6, vcc
	v_add_u32_e32 v6, 1, v2
	v_cmp_ge_u32_e32 vcc, v5, v3
	s_nop 1
	v_cndmask_b32_e32 v2, v2, v6, vcc
	v_mul_lo_u32 v5, v3, v2
	v_add_u32_e32 v3, v5, v3
	v_cmp_ne_u32_e32 vcc, v4, v3
	s_and_saveexec_b64 s[6:7], vcc
	s_xor_b64 s[6:7], exec, s[6:7]
	s_cbranch_execz .LBB0_179
	s_waitcnt lgkmcnt(0)
	s_add_u32 s12, s78, 0x83500
	s_addc_u32 s13, s79, 0
	v_mov_b32_e32 v1, 0
	global_load_dword v1, v1, s[12:13] sc1
	s_waitcnt vmcnt(0)
	v_cmp_gt_u32_e32 vcc, 2, v1
	s_and_saveexec_b64 s[8:9], vcc
	s_cbranch_execz .LBB0_178
	s_add_u32 s10, s78, 0x80200
	s_addc_u32 s11, s79, 0
	s_mov_b32 s24, 1
	s_mov_b64 s[14:15], 0
	v_mov_b32_e32 v1, 0
	s_branch .LBB0_169

; __device__ __forceinline__ unsigned xb_ld(unsigned* p)              { return __hip_atomic_load(p, __ATOMIC_RELAXED, __HIP_MEMORY_SCOPE_AGENT); }
; #define XB_SPIN(cond, bar) do { unsigned _sp = 0; while (cond) { __builtin_amdgcn_s_sleep(1); \
;     if ((++_sp & 255u) == 0u) { if (xb_ld(&(bar)[XB_TMO])) break; if (_sp > XB_SPIN_CAP) { atomicAdd(&(bar)[XB_TMO], 1u); break; } } } } while (0)
; __device__ __forceinline__ void xcd_barrier(const XcdBarrier& b) {
;     ...
;             XB_SPIN(xb_ld(&bar[XB_XGEN(b.x)]) == gen, bar);
.LBB0_173:
	global_load_dword v3, v1, s[12:13] sc1
	s_add_i32 s24, s24, 1
	s_mov_b64 s[20:21], -1
	s_waitcnt vmcnt(0)
	v_cmp_le_u32_e32 vcc, 2, v3
	s_orn2_b64 s[18:19], vcc, exec
	s_branch .LBB0_168

; __device__ __forceinline__ unsigned xb_ld(unsigned* p)              { return __hip_atomic_load(p, __ATOMIC_RELAXED, __HIP_MEMORY_SCOPE_AGENT); }
; __device__ __forceinline__ unsigned xb_add(unsigned* p, unsigned v) { return __hip_atomic_fetch_add(p, v, __ATOMIC_RELAXED, __HIP_MEMORY_SCOPE_AGENT); }
; #define XB_SPIN(cond, bar) do { unsigned _sp = 0; while (cond) { __builtin_amdgcn_s_sleep(1); \
;     if ((++_sp & 255u) == 0u) { if (xb_ld(&(bar)[XB_TMO])) break; if (_sp > XB_SPIN_CAP) { atomicAdd(&(bar)[XB_TMO], 1u); break; } } } } while (0)
; __device__ __forceinline__ void xcd_barrier(const XcdBarrier& b) {
;     ...
;         unsigned nloc = b.st[0], nx = b.st[1];
;         if (nloc == 0u) { xcd_barrier_complete(bar, b.x, nloc, nx); b.st[0] = nloc; b.st[1] = nx; }
;         const unsigned old = xb_add(&bar[XB_XSUB(b.x)], 1u);
;         const unsigned gen = old / nloc;
;         if (old + 1u == (gen + 1u) * nloc) {
;             __builtin_amdgcn_fence(__ATOMIC_RELEASE, "agent");
;             asm volatile("s_waitcnt vmcnt(0)" ::: "memory");
;             const unsigned og = xb_add(&bar[XB_TOP], 1u);
;             const unsigned tg = og / nx;
;             if (og + 1u == (tg + 1u) * nx) xb_add(&bar[XB_TOPGEN], 1u);
;             else XB_SPIN(xb_ld(&bar[XB_TOPGEN]) == tg, bar);
;             __builtin_amdgcn_fence(__ATOMIC_ACQUIRE, "agent");
;             xb_add(&bar[XB_XGEN(b.x)], 1u);
;             asm volatile("s_waitcnt vmcnt(0)" ::: "memory");
;         } else {
;             XB_SPIN(xb_ld(&bar[XB_XGEN(b.x)]) == gen, bar);
.LBB0_232:
	s_lshl_b32 s4, s58, 8
	v_readlane_b32 s6, v254, 5
	v_readlane_b32 s7, v254, 6
	s_add_u32 s4, s6, s4
	s_addc_u32 s5, s7, 0
	v_mov_b32_e32 v2, 0x1000
	v_mov_b32_e32 v4, 1
	global_atomic_add v4, v2, v4, s[4:5] offset:1024 sc0
	v_cvt_f32_u32_e32 v2, v3
	v_sub_u32_e32 v5, 0, v3
	v_rcp_iflag_f32_e32 v2, v2
	s_nop 0
	v_mul_f32_e32 v2, 0x4f7ffffe, v2
	v_cvt_u32_f32_e32 v2, v2
	v_mul_lo_u32 v5, v5, v2
	v_mul_hi_u32 v5, v2, v5
	v_add_u32_e32 v2, v2, v5
	s_waitcnt vmcnt(0)
	v_mul_hi_u32 v2, v4, v2
	v_mul_lo_u32 v5, v2, v3
	v_sub_u32_e32 v5, v4, v5
	v_add_u32_e32 v6, 1, v2
	v_cmp_ge_u32_e32 vcc, v5, v3
	v_add_u32_e32 v4, 1, v4
	s_nop 0
	v_cndmask_b32_e32 v2, v2, v6, vcc
	v_sub_u32_e32 v6, v5, v3
	v_cndmask_b32_e32 v5, v5, v6, vcc
	v_add_u32_e32 v6, 1, v2
	v_cmp_ge_u32_e32 vcc, v5, v3
	s_nop 1
	v_cndmask_b32_e32 v2, v2, v6, vcc
	v_mul_lo_u32 v5, v3, v2
	v_add_u32_e32 v3, v5, v3
	v_cmp_ne_u32_e32 vcc, v4, v3
	s_and_saveexec_b64 s[6:7], vcc
	s_xor_b64 s[6:7], exec, s[6:7]
	s_cbranch_execz .LBB0_246
	s_waitcnt lgkmcnt(0)
	s_add_u32 s12, s78, 0x83500
	s_addc_u32 s13, s79, 0
	v_mov_b32_e32 v1, 0
	global_load_dword v1, v1, s[12:13] sc1
	s_waitcnt vmcnt(0)
	v_cmp_gt_u32_e32 vcc, 3, v1
	s_and_saveexec_b64 s[8:9], vcc
	s_cbranch_execz .LBB0_245
	s_add_u32 s10, s78, 0x80200
	s_addc_u32 s11, s79, 0
	s_mov_b32 s24, 1
	s_mov_b64 s[14:15], 0
	v_mov_b32_e32 v1, 0
	s_branch .LBB0_236

; __device__ __forceinline__ unsigned xb_ld(unsigned* p)              { return __hip_atomic_load(p, __ATOMIC_RELAXED, __HIP_MEMORY_SCOPE_AGENT); }
; #define XB_SPIN(cond, bar) do { unsigned _sp = 0; while (cond) { __builtin_amdgcn_s_sleep(1); \
;     if ((++_sp & 255u) == 0u) { if (xb_ld(&(bar)[XB_TMO])) break; if (_sp > XB_SPIN_CAP) { atomicAdd(&(bar)[XB_TMO], 1u); break; } } } } while (0)
; __device__ __forceinline__ void xcd_barrier(const XcdBarrier& b) {
;     ...
;             XB_SPIN(xb_ld(&bar[XB_XGEN(b.x)]) == gen, bar);
.LBB0_240:
	global_load_dword v3, v1, s[12:13] sc1
	s_add_i32 s24, s24, 1
	s_mov_b64 s[20:21], -1
	s_waitcnt vmcnt(0)
	v_cmp_le_u32_e32 vcc, 3, v3
	s_orn2_b64 s[18:19], vcc, exec
	s_branch .LBB0_235

; __device__ __forceinline__ unsigned xb_ld(unsigned* p)              { return __hip_atomic_load(p, __ATOMIC_RELAXED, __HIP_MEMORY_SCOPE_AGENT); }
; __device__ __forceinline__ unsigned xb_add(unsigned* p, unsigned v) { return __hip_atomic_fetch_add(p, v, __ATOMIC_RELAXED, __HIP_MEMORY_SCOPE_AGENT); }
; #define XB_SPIN(cond, bar) do { unsigned _sp = 0; while (cond) { __builtin_amdgcn_s_sleep(1); \
;     if ((++_sp & 255u) == 0u) { if (xb_ld(&(bar)[XB_TMO])) break; if (_sp > XB_SPIN_CAP) { atomicAdd(&(bar)[XB_TMO], 1u); break; } } } } while (0)
; __device__ __forceinline__ void xcd_barrier(const XcdBarrier& b) {
;     ...
;         unsigned nloc = b.st[0], nx = b.st[1];
;         if (nloc == 0u) { xcd_barrier_complete(bar, b.x, nloc, nx); b.st[0] = nloc; b.st[1] = nx; }
;         const unsigned old = xb_add(&bar[XB_XSUB(b.x)], 1u);
;         const unsigned gen = old / nloc;
;         if (old + 1u == (gen + 1u) * nloc) {
;             __builtin_amdgcn_fence(__ATOMIC_RELEASE, "agent");
;             asm volatile("s_waitcnt vmcnt(0)" ::: "memory");
;             const unsigned og = xb_add(&bar[XB_TOP], 1u);
;             const unsigned tg = og / nx;
;             if (og + 1u == (tg + 1u) * nx) xb_add(&bar[XB_TOPGEN], 1u);
;             else XB_SPIN(xb_ld(&bar[XB_TOPGEN]) == tg, bar);
;             __builtin_amdgcn_fence(__ATOMIC_ACQUIRE, "agent");
;             xb_add(&bar[XB_XGEN(b.x)], 1u);
;             asm volatile("s_waitcnt vmcnt(0)" ::: "memory");
;         } else {
;             XB_SPIN(xb_ld(&bar[XB_XGEN(b.x)]) == gen, bar);
.LBB0_393:
	s_lshl_b32 s4, s58, 8
	v_readlane_b32 s6, v254, 5
	v_readlane_b32 s7, v254, 6
	s_add_u32 s4, s6, s4
	s_addc_u32 s5, s7, 0
	v_mov_b32_e32 v2, 0x1000
	v_mov_b32_e32 v4, 1
	global_atomic_add v4, v2, v4, s[4:5] offset:1024 sc0
	v_cvt_f32_u32_e32 v2, v3
	v_sub_u32_e32 v5, 0, v3
	v_rcp_iflag_f32_e32 v2, v2
	s_nop 0
	v_mul_f32_e32 v2, 0x4f7ffffe, v2
	v_cvt_u32_f32_e32 v2, v2
	v_mul_lo_u32 v5, v5, v2
	v_mul_hi_u32 v5, v2, v5
	v_add_u32_e32 v2, v2, v5
	s_waitcnt vmcnt(0)
	v_mul_hi_u32 v2, v4, v2
	v_mul_lo_u32 v5, v2, v3
	v_sub_u32_e32 v5, v4, v5
	v_add_u32_e32 v6, 1, v2
	v_cmp_ge_u32_e32 vcc, v5, v3
	v_add_u32_e32 v4, 1, v4
	s_nop 0
	v_cndmask_b32_e32 v2, v2, v6, vcc
	v_sub_u32_e32 v6, v5, v3
	v_cndmask_b32_e32 v5, v5, v6, vcc
	v_add_u32_e32 v6, 1, v2
	v_cmp_ge_u32_e32 vcc, v5, v3
	s_nop 1
	v_cndmask_b32_e32 v2, v2, v6, vcc
	v_mul_lo_u32 v5, v3, v2
	v_add_u32_e32 v3, v5, v3
	v_cmp_ne_u32_e32 vcc, v4, v3
	s_and_saveexec_b64 s[6:7], vcc
	s_xor_b64 s[6:7], exec, s[6:7]
	s_cbranch_execz .LBB0_407
	s_waitcnt lgkmcnt(0)
	s_add_u32 s14, s78, 0x83500
	s_addc_u32 s15, s79, 0
	v_mov_b32_e32 v1, 0
	global_load_dword v1, v1, s[14:15] sc1
	s_waitcnt vmcnt(0)
	v_cmp_gt_u32_e32 vcc, 4, v1
	s_and_saveexec_b64 s[8:9], vcc
	s_cbranch_execz .LBB0_406
	s_add_u32 s10, s78, 0x80200
	s_addc_u32 s11, s79, 0
	s_mov_b32 s26, 1
	s_mov_b64 s[16:17], 0
	v_mov_b32_e32 v1, 0
	s_branch .LBB0_397

; __device__ __forceinline__ unsigned xb_ld(unsigned* p)              { return __hip_atomic_load(p, __ATOMIC_RELAXED, __HIP_MEMORY_SCOPE_AGENT); }
; #define XB_SPIN(cond, bar) do { unsigned _sp = 0; while (cond) { __builtin_amdgcn_s_sleep(1); \
;     if ((++_sp & 255u) == 0u) { if (xb_ld(&(bar)[XB_TMO])) break; if (_sp > XB_SPIN_CAP) { atomicAdd(&(bar)[XB_TMO], 1u); break; } } } } while (0)
; __device__ __forceinline__ void xcd_barrier(const XcdBarrier& b) {
;     ...
;             XB_SPIN(xb_ld(&bar[XB_XGEN(b.x)]) == gen, bar);
.LBB0_401:
	global_load_dword v3, v1, s[14:15] sc1
	s_add_i32 s26, s26, 1
	s_mov_b64 s[22:23], -1
	s_waitcnt vmcnt(0)
	v_cmp_le_u32_e32 vcc, 4, v3
	s_orn2_b64 s[20:21], vcc, exec
	s_branch .LBB0_396

; __device__ __forceinline__ unsigned xb_ld(unsigned* p)              { return __hip_atomic_load(p, __ATOMIC_RELAXED, __HIP_MEMORY_SCOPE_AGENT); }
; __device__ __forceinline__ unsigned xb_add(unsigned* p, unsigned v) { return __hip_atomic_fetch_add(p, v, __ATOMIC_RELAXED, __HIP_MEMORY_SCOPE_AGENT); }
; #define XB_SPIN(cond, bar) do { unsigned _sp = 0; while (cond) { __builtin_amdgcn_s_sleep(1); \
;     if ((++_sp & 255u) == 0u) { if (xb_ld(&(bar)[XB_TMO])) break; if (_sp > XB_SPIN_CAP) { atomicAdd(&(bar)[XB_TMO], 1u); break; } } } } while (0)
; __device__ __forceinline__ void xcd_barrier(const XcdBarrier& b) {
;     ...
;         unsigned nloc = b.st[0], nx = b.st[1];
;         if (nloc == 0u) { xcd_barrier_complete(bar, b.x, nloc, nx); b.st[0] = nloc; b.st[1] = nx; }
;         const unsigned old = xb_add(&bar[XB_XSUB(b.x)], 1u);
;         const unsigned gen = old / nloc;
;         if (old + 1u == (gen + 1u) * nloc) {
;             __builtin_amdgcn_fence(__ATOMIC_RELEASE, "agent");
;             asm volatile("s_waitcnt vmcnt(0)" ::: "memory");
;             const unsigned og = xb_add(&bar[XB_TOP], 1u);
;             const unsigned tg = og / nx;
;             if (og + 1u == (tg + 1u) * nx) xb_add(&bar[XB_TOPGEN], 1u);
;             else XB_SPIN(xb_ld(&bar[XB_TOPGEN]) == tg, bar);
;             __builtin_amdgcn_fence(__ATOMIC_ACQUIRE, "agent");
;             xb_add(&bar[XB_XGEN(b.x)], 1u);
;             asm volatile("s_waitcnt vmcnt(0)" ::: "memory");
;         } else {
;             XB_SPIN(xb_ld(&bar[XB_XGEN(b.x)]) == gen, bar);
.LBB0_595:
	s_lshl_b32 s4, s50, 8
	v_readlane_b32 s6, v254, 5
	v_readlane_b32 s7, v254, 6
	s_add_u32 s4, s6, s4
	s_addc_u32 s5, s7, 0
	v_mov_b32_e32 v2, 0x1000
	v_mov_b32_e32 v4, 1
	global_atomic_add v4, v2, v4, s[4:5] offset:1024 sc0
	v_cvt_f32_u32_e32 v2, v3
	v_sub_u32_e32 v5, 0, v3
	v_rcp_iflag_f32_e32 v2, v2
	s_nop 0
	v_mul_f32_e32 v2, 0x4f7ffffe, v2
	v_cvt_u32_f32_e32 v2, v2
	v_mul_lo_u32 v5, v5, v2
	v_mul_hi_u32 v5, v2, v5
	v_add_u32_e32 v2, v2, v5
	s_waitcnt vmcnt(0)
	v_mul_hi_u32 v2, v4, v2
	v_mul_lo_u32 v5, v2, v3
	v_sub_u32_e32 v5, v4, v5
	v_add_u32_e32 v6, 1, v2
	v_cmp_ge_u32_e32 vcc, v5, v3
	v_add_u32_e32 v4, 1, v4
	s_nop 0
	v_cndmask_b32_e32 v2, v2, v6, vcc
	v_sub_u32_e32 v6, v5, v3
	v_cndmask_b32_e32 v5, v5, v6, vcc
	v_add_u32_e32 v6, 1, v2
	v_cmp_ge_u32_e32 vcc, v5, v3
	s_nop 1
	v_cndmask_b32_e32 v2, v2, v6, vcc
	v_mul_lo_u32 v5, v3, v2
	v_add_u32_e32 v3, v5, v3
	v_cmp_ne_u32_e32 vcc, v4, v3
	s_and_saveexec_b64 s[6:7], vcc
	s_xor_b64 s[6:7], exec, s[6:7]
	s_cbranch_execz .LBB0_609
	s_waitcnt lgkmcnt(0)
	s_add_u32 s14, s78, 0x83500
	s_addc_u32 s15, s79, 0
	v_mov_b32_e32 v1, 0
	global_load_dword v1, v1, s[14:15] sc1
	s_waitcnt vmcnt(0)
	v_cmp_gt_u32_e32 vcc, 5, v1
	s_and_saveexec_b64 s[8:9], vcc
	s_cbranch_execz .LBB0_608
	s_add_u32 s10, s78, 0x80200
	s_addc_u32 s11, s79, 0
	s_mov_b32 s26, 1
	s_mov_b64 s[16:17], 0
	v_mov_b32_e32 v1, 0
	s_branch .LBB0_599

; __device__ __forceinline__ unsigned xb_ld(unsigned* p)              { return __hip_atomic_load(p, __ATOMIC_RELAXED, __HIP_MEMORY_SCOPE_AGENT); }
; #define XB_SPIN(cond, bar) do { unsigned _sp = 0; while (cond) { __builtin_amdgcn_s_sleep(1); \
;     if ((++_sp & 255u) == 0u) { if (xb_ld(&(bar)[XB_TMO])) break; if (_sp > XB_SPIN_CAP) { atomicAdd(&(bar)[XB_TMO], 1u); break; } } } } while (0)
; __device__ __forceinline__ void xcd_barrier(const XcdBarrier& b) {
;     ...
;             XB_SPIN(xb_ld(&bar[XB_XGEN(b.x)]) == gen, bar);
.LBB0_603:
	global_load_dword v3, v1, s[14:15] sc1
	s_add_i32 s26, s26, 1
	s_mov_b64 s[22:23], -1
	s_waitcnt vmcnt(0)
	v_cmp_le_u32_e32 vcc, 5, v3
	s_orn2_b64 s[20:21], vcc, exec
	s_branch .LBB0_598

; __device__ __forceinline__ unsigned xb_ld(unsigned* p)              { return __hip_atomic_load(p, __ATOMIC_RELAXED, __HIP_MEMORY_SCOPE_AGENT); }
; __device__ __forceinline__ unsigned xb_add(unsigned* p, unsigned v) { return __hip_atomic_fetch_add(p, v, __ATOMIC_RELAXED, __HIP_MEMORY_SCOPE_AGENT); }
; #define XB_SPIN(cond, bar) do { unsigned _sp = 0; while (cond) { __builtin_amdgcn_s_sleep(1); \
;     if ((++_sp & 255u) == 0u) { if (xb_ld(&(bar)[XB_TMO])) break; if (_sp > XB_SPIN_CAP) { atomicAdd(&(bar)[XB_TMO], 1u); break; } } } } while (0)
; __device__ __forceinline__ void xcd_barrier(const XcdBarrier& b) {
;     ...
;         unsigned nloc = b.st[0], nx = b.st[1];
;         if (nloc == 0u) { xcd_barrier_complete(bar, b.x, nloc, nx); b.st[0] = nloc; b.st[1] = nx; }
;         const unsigned old = xb_add(&bar[XB_XSUB(b.x)], 1u);
;         const unsigned gen = old / nloc;
;         if (old + 1u == (gen + 1u) * nloc) {
;             __builtin_amdgcn_fence(__ATOMIC_RELEASE, "agent");
;             asm volatile("s_waitcnt vmcnt(0)" ::: "memory");
;             const unsigned og = xb_add(&bar[XB_TOP], 1u);
;             const unsigned tg = og / nx;
;             if (og + 1u == (tg + 1u) * nx) xb_add(&bar[XB_TOPGEN], 1u);
;             else XB_SPIN(xb_ld(&bar[XB_TOPGEN]) == tg, bar);
;             __builtin_amdgcn_fence(__ATOMIC_ACQUIRE, "agent");
;             xb_add(&bar[XB_XGEN(b.x)], 1u);
;             asm volatile("s_waitcnt vmcnt(0)" ::: "memory");
;         } else {
;             XB_SPIN(xb_ld(&bar[XB_XGEN(b.x)]) == gen, bar);
.LBB0_670:
	s_lshl_b32 s4, s50, 8
	v_readlane_b32 s6, v254, 5
	v_readlane_b32 s7, v254, 6
	s_add_u32 s4, s6, s4
	s_addc_u32 s5, s7, 0
	v_mov_b32_e32 v2, 0x1000
	v_mov_b32_e32 v4, 1
	global_atomic_add v4, v2, v4, s[4:5] offset:1024 sc0
	v_cvt_f32_u32_e32 v2, v3
	v_sub_u32_e32 v5, 0, v3
	v_rcp_iflag_f32_e32 v2, v2
	s_nop 0
	v_mul_f32_e32 v2, 0x4f7ffffe, v2
	v_cvt_u32_f32_e32 v2, v2
	v_mul_lo_u32 v5, v5, v2
	v_mul_hi_u32 v5, v2, v5
	v_add_u32_e32 v2, v2, v5
	s_waitcnt vmcnt(0)
	v_mul_hi_u32 v2, v4, v2
	v_mul_lo_u32 v5, v2, v3
	v_sub_u32_e32 v5, v4, v5
	v_add_u32_e32 v6, 1, v2
	v_cmp_ge_u32_e32 vcc, v5, v3
	v_add_u32_e32 v4, 1, v4
	s_nop 0
	v_cndmask_b32_e32 v2, v2, v6, vcc
	v_sub_u32_e32 v6, v5, v3
	v_cndmask_b32_e32 v5, v5, v6, vcc
	v_add_u32_e32 v6, 1, v2
	v_cmp_ge_u32_e32 vcc, v5, v3
	s_nop 1
	v_cndmask_b32_e32 v2, v2, v6, vcc
	v_mul_lo_u32 v5, v3, v2
	v_add_u32_e32 v3, v5, v3
	v_cmp_ne_u32_e32 vcc, v4, v3
	s_and_saveexec_b64 s[6:7], vcc
	s_xor_b64 s[6:7], exec, s[6:7]
	s_cbranch_execz .LBB0_684
	s_waitcnt lgkmcnt(0)
	s_add_u32 s14, s78, 0x83500
	s_addc_u32 s15, s79, 0
	v_mov_b32_e32 v1, 0
	global_load_dword v1, v1, s[14:15] sc1
	s_waitcnt vmcnt(0)
	v_cmp_gt_u32_e32 vcc, 6, v1
	s_and_saveexec_b64 s[8:9], vcc
	s_cbranch_execz .LBB0_683
	s_add_u32 s10, s78, 0x80200
	s_addc_u32 s11, s79, 0
	s_mov_b32 s26, 1
	s_mov_b64 s[16:17], 0
	v_mov_b32_e32 v1, 0
	s_branch .LBB0_674

; __device__ __forceinline__ unsigned xb_ld(unsigned* p)              { return __hip_atomic_load(p, __ATOMIC_RELAXED, __HIP_MEMORY_SCOPE_AGENT); }
; #define XB_SPIN(cond, bar) do { unsigned _sp = 0; while (cond) { __builtin_amdgcn_s_sleep(1); \
;     if ((++_sp & 255u) == 0u) { if (xb_ld(&(bar)[XB_TMO])) break; if (_sp > XB_SPIN_CAP) { atomicAdd(&(bar)[XB_TMO], 1u); break; } } } } while (0)
; __device__ __forceinline__ void xcd_barrier(const XcdBarrier& b) {
;     ...
;             XB_SPIN(xb_ld(&bar[XB_XGEN(b.x)]) == gen, bar);
.LBB0_678:
	global_load_dword v3, v1, s[14:15] sc1
	s_add_i32 s26, s26, 1
	s_mov_b64 s[22:23], -1
	s_waitcnt vmcnt(0)
	v_cmp_le_u32_e32 vcc, 6, v3
	s_orn2_b64 s[20:21], vcc, exec
	s_branch .LBB0_673

; __device__ __forceinline__ unsigned xb_ld(unsigned* p)              { return __hip_atomic_load(p, __ATOMIC_RELAXED, __HIP_MEMORY_SCOPE_AGENT); }
; __device__ __forceinline__ unsigned xb_add(unsigned* p, unsigned v) { return __hip_atomic_fetch_add(p, v, __ATOMIC_RELAXED, __HIP_MEMORY_SCOPE_AGENT); }
; #define XB_SPIN(cond, bar) do { unsigned _sp = 0; while (cond) { __builtin_amdgcn_s_sleep(1); \
;     if ((++_sp & 255u) == 0u) { if (xb_ld(&(bar)[XB_TMO])) break; if (_sp > XB_SPIN_CAP) { atomicAdd(&(bar)[XB_TMO], 1u); break; } } } } while (0)
; __device__ __forceinline__ void xcd_barrier(const XcdBarrier& b) {
;     ...
;         unsigned nloc = b.st[0], nx = b.st[1];
;         if (nloc == 0u) { xcd_barrier_complete(bar, b.x, nloc, nx); b.st[0] = nloc; b.st[1] = nx; }
;         const unsigned old = xb_add(&bar[XB_XSUB(b.x)], 1u);
;         const unsigned gen = old / nloc;
;         if (old + 1u == (gen + 1u) * nloc) {
;             __builtin_amdgcn_fence(__ATOMIC_RELEASE, "agent");
;             asm volatile("s_waitcnt vmcnt(0)" ::: "memory");
;             const unsigned og = xb_add(&bar[XB_TOP], 1u);
;             const unsigned tg = og / nx;
;             if (og + 1u == (tg + 1u) * nx) xb_add(&bar[XB_TOPGEN], 1u);
;             else XB_SPIN(xb_ld(&bar[XB_TOPGEN]) == tg, bar);
;             __builtin_amdgcn_fence(__ATOMIC_ACQUIRE, "agent");
;             xb_add(&bar[XB_XGEN(b.x)], 1u);
;             asm volatile("s_waitcnt vmcnt(0)" ::: "memory");
;         } else {
;             XB_SPIN(xb_ld(&bar[XB_XGEN(b.x)]) == gen, bar);
.LBB0_785:
	s_lshl_b32 s4, s50, 8
	v_readlane_b32 s6, v254, 5
	v_readlane_b32 s7, v254, 6
	s_add_u32 s4, s6, s4
	s_addc_u32 s5, s7, 0
	v_mov_b32_e32 v2, 0x1000
	v_mov_b32_e32 v4, 1
	global_atomic_add v4, v2, v4, s[4:5] offset:1024 sc0
	v_cvt_f32_u32_e32 v2, v3
	v_sub_u32_e32 v5, 0, v3
	v_rcp_iflag_f32_e32 v2, v2
	s_nop 0
	v_mul_f32_e32 v2, 0x4f7ffffe, v2
	v_cvt_u32_f32_e32 v2, v2
	v_mul_lo_u32 v5, v5, v2
	v_mul_hi_u32 v5, v2, v5
	v_add_u32_e32 v2, v2, v5
	s_waitcnt vmcnt(0)
	v_mul_hi_u32 v2, v4, v2
	v_mul_lo_u32 v5, v2, v3
	v_sub_u32_e32 v5, v4, v5
	v_add_u32_e32 v6, 1, v2
	v_cmp_ge_u32_e32 vcc, v5, v3
	v_add_u32_e32 v4, 1, v4
	s_nop 0
	v_cndmask_b32_e32 v2, v2, v6, vcc
	v_sub_u32_e32 v6, v5, v3
	v_cndmask_b32_e32 v5, v5, v6, vcc
	v_add_u32_e32 v6, 1, v2
	v_cmp_ge_u32_e32 vcc, v5, v3
	s_nop 1
	v_cndmask_b32_e32 v2, v2, v6, vcc
	v_mul_lo_u32 v5, v3, v2
	v_add_u32_e32 v3, v5, v3
	v_cmp_ne_u32_e32 vcc, v4, v3
	s_and_saveexec_b64 s[6:7], vcc
	s_xor_b64 s[6:7], exec, s[6:7]
	s_cbranch_execz .LBB0_799
	s_waitcnt lgkmcnt(0)
	s_add_u32 s14, s78, 0x83500
	s_addc_u32 s15, s79, 0
	v_mov_b32_e32 v1, 0
	global_load_dword v1, v1, s[14:15] sc1
	s_waitcnt vmcnt(0)
	v_cmp_gt_u32_e32 vcc, 7, v1
	s_and_saveexec_b64 s[8:9], vcc
	s_cbranch_execz .LBB0_798
	s_add_u32 s10, s78, 0x80200
	s_addc_u32 s11, s79, 0
	s_mov_b32 s26, 1
	s_mov_b64 s[16:17], 0
	v_mov_b32_e32 v1, 0
	s_branch .LBB0_789

; __device__ __forceinline__ unsigned xb_ld(unsigned* p)              { return __hip_atomic_load(p, __ATOMIC_RELAXED, __HIP_MEMORY_SCOPE_AGENT); }
; #define XB_SPIN(cond, bar) do { unsigned _sp = 0; while (cond) { __builtin_amdgcn_s_sleep(1); \
;     if ((++_sp & 255u) == 0u) { if (xb_ld(&(bar)[XB_TMO])) break; if (_sp > XB_SPIN_CAP) { atomicAdd(&(bar)[XB_TMO], 1u); break; } } } } while (0)
; __device__ __forceinline__ void xcd_barrier(const XcdBarrier& b) {
;     ...
;             XB_SPIN(xb_ld(&bar[XB_XGEN(b.x)]) == gen, bar);
.LBB0_793:
	global_load_dword v3, v1, s[14:15] sc1
	s_add_i32 s26, s26, 1
	s_mov_b64 s[22:23], -1
	s_waitcnt vmcnt(0)
	v_cmp_le_u32_e32 vcc, 7, v3
	s_orn2_b64 s[20:21], vcc, exec
	s_branch .LBB0_788

; __device__ __forceinline__ unsigned xb_ld(unsigned* p)              { return __hip_atomic_load(p, __ATOMIC_RELAXED, __HIP_MEMORY_SCOPE_AGENT); }
; __device__ __forceinline__ unsigned xb_add(unsigned* p, unsigned v) { return __hip_atomic_fetch_add(p, v, __ATOMIC_RELAXED, __HIP_MEMORY_SCOPE_AGENT); }
; #define XB_SPIN(cond, bar) do { unsigned _sp = 0; while (cond) { __builtin_amdgcn_s_sleep(1); \
;     if ((++_sp & 255u) == 0u) { if (xb_ld(&(bar)[XB_TMO])) break; if (_sp > XB_SPIN_CAP) { atomicAdd(&(bar)[XB_TMO], 1u); break; } } } } while (0)
; __device__ __forceinline__ void xcd_barrier(const XcdBarrier& b) {
;     ...
;         unsigned nloc = b.st[0], nx = b.st[1];
;         if (nloc == 0u) { xcd_barrier_complete(bar, b.x, nloc, nx); b.st[0] = nloc; b.st[1] = nx; }
;         const unsigned old = xb_add(&bar[XB_XSUB(b.x)], 1u);
;         const unsigned gen = old / nloc;
;         if (old + 1u == (gen + 1u) * nloc) {
;             __builtin_amdgcn_fence(__ATOMIC_RELEASE, "agent");
;             asm volatile("s_waitcnt vmcnt(0)" ::: "memory");
;             const unsigned og = xb_add(&bar[XB_TOP], 1u);
;             const unsigned tg = og / nx;
;             if (og + 1u == (tg + 1u) * nx) xb_add(&bar[XB_TOPGEN], 1u);
;             else XB_SPIN(xb_ld(&bar[XB_TOPGEN]) == tg, bar);
;             __builtin_amdgcn_fence(__ATOMIC_ACQUIRE, "agent");
;             xb_add(&bar[XB_XGEN(b.x)], 1u);
;             asm volatile("s_waitcnt vmcnt(0)" ::: "memory");
;         } else {
;             XB_SPIN(xb_ld(&bar[XB_XGEN(b.x)]) == gen, bar);
.LBB0_942:
	s_lshl_b32 s4, s50, 8
	v_readlane_b32 s6, v254, 5
	v_readlane_b32 s7, v254, 6
	s_add_u32 s4, s6, s4
	s_addc_u32 s5, s7, 0
	v_mov_b32_e32 v2, 0x1000
	v_mov_b32_e32 v4, 1
	global_atomic_add v4, v2, v4, s[4:5] offset:1024 sc0
	v_cvt_f32_u32_e32 v2, v3
	v_sub_u32_e32 v5, 0, v3
	v_rcp_iflag_f32_e32 v2, v2
	s_nop 0
	v_mul_f32_e32 v2, 0x4f7ffffe, v2
	v_cvt_u32_f32_e32 v2, v2
	v_mul_lo_u32 v5, v5, v2
	v_mul_hi_u32 v5, v2, v5
	v_add_u32_e32 v2, v2, v5
	s_waitcnt vmcnt(0)
	v_mul_hi_u32 v2, v4, v2
	v_mul_lo_u32 v5, v2, v3
	v_sub_u32_e32 v5, v4, v5
	v_add_u32_e32 v6, 1, v2
	v_cmp_ge_u32_e32 vcc, v5, v3
	v_add_u32_e32 v4, 1, v4
	s_nop 0
	v_cndmask_b32_e32 v2, v2, v6, vcc
	v_sub_u32_e32 v6, v5, v3
	v_cndmask_b32_e32 v5, v5, v6, vcc
	v_add_u32_e32 v6, 1, v2
	v_cmp_ge_u32_e32 vcc, v5, v3
	s_nop 1
	v_cndmask_b32_e32 v2, v2, v6, vcc
	v_mul_lo_u32 v5, v3, v2
	v_add_u32_e32 v3, v5, v3
	v_cmp_ne_u32_e32 vcc, v4, v3
	s_and_saveexec_b64 s[6:7], vcc
	s_xor_b64 s[6:7], exec, s[6:7]
	s_cbranch_execz .LBB0_956
	s_waitcnt lgkmcnt(0)
	s_add_u32 s14, s78, 0x83500
	s_addc_u32 s15, s79, 0
	v_mov_b32_e32 v1, 0
	global_load_dword v1, v1, s[14:15] sc1
	s_waitcnt vmcnt(0)
	v_cmp_gt_u32_e32 vcc, 8, v1
	s_and_saveexec_b64 s[8:9], vcc
	s_cbranch_execz .LBB0_955
	s_add_u32 s10, s78, 0x80200
	s_addc_u32 s11, s79, 0
	s_mov_b32 s26, 1
	s_mov_b64 s[16:17], 0
	v_mov_b32_e32 v1, 0
	s_branch .LBB0_946

; __device__ __forceinline__ unsigned xb_ld(unsigned* p)              { return __hip_atomic_load(p, __ATOMIC_RELAXED, __HIP_MEMORY_SCOPE_AGENT); }
; #define XB_SPIN(cond, bar) do { unsigned _sp = 0; while (cond) { __builtin_amdgcn_s_sleep(1); \
;     if ((++_sp & 255u) == 0u) { if (xb_ld(&(bar)[XB_TMO])) break; if (_sp > XB_SPIN_CAP) { atomicAdd(&(bar)[XB_TMO], 1u); break; } } } } while (0)
; __device__ __forceinline__ void xcd_barrier(const XcdBarrier& b) {
;     ...
;             XB_SPIN(xb_ld(&bar[XB_XGEN(b.x)]) == gen, bar);
.LBB0_950:
	global_load_dword v3, v1, s[14:15] sc1
	s_add_i32 s26, s26, 1
	s_mov_b64 s[22:23], -1
	s_waitcnt vmcnt(0)
	v_cmp_le_u32_e32 vcc, 8, v3
	s_orn2_b64 s[20:21], vcc, exec
	s_branch .LBB0_945

; __device__ __forceinline__ unsigned xb_ld(unsigned* p)              { return __hip_atomic_load(p, __ATOMIC_RELAXED, __HIP_MEMORY_SCOPE_AGENT); }
; __device__ __forceinline__ unsigned xb_add(unsigned* p, unsigned v) { return __hip_atomic_fetch_add(p, v, __ATOMIC_RELAXED, __HIP_MEMORY_SCOPE_AGENT); }
; #define XB_SPIN(cond, bar) do { unsigned _sp = 0; while (cond) { __builtin_amdgcn_s_sleep(1); \
;     if ((++_sp & 255u) == 0u) { if (xb_ld(&(bar)[XB_TMO])) break; if (_sp > XB_SPIN_CAP) { atomicAdd(&(bar)[XB_TMO], 1u); break; } } } } while (0)
; __device__ __forceinline__ void xcd_barrier(const XcdBarrier& b) {
;     ...
;         unsigned nloc = b.st[0], nx = b.st[1];
;         if (nloc == 0u) { xcd_barrier_complete(bar, b.x, nloc, nx); b.st[0] = nloc; b.st[1] = nx; }
;         const unsigned old = xb_add(&bar[XB_XSUB(b.x)], 1u);
;         const unsigned gen = old / nloc;
;         if (old + 1u == (gen + 1u) * nloc) {
;             __builtin_amdgcn_fence(__ATOMIC_RELEASE, "agent");
;             asm volatile("s_waitcnt vmcnt(0)" ::: "memory");
;             const unsigned og = xb_add(&bar[XB_TOP], 1u);
;             const unsigned tg = og / nx;
;             if (og + 1u == (tg + 1u) * nx) xb_add(&bar[XB_TOPGEN], 1u);
;             else XB_SPIN(xb_ld(&bar[XB_TOPGEN]) == tg, bar);
;             __builtin_amdgcn_fence(__ATOMIC_ACQUIRE, "agent");
;             xb_add(&bar[XB_XGEN(b.x)], 1u);
;             asm volatile("s_waitcnt vmcnt(0)" ::: "memory");
;         } else {
;             XB_SPIN(xb_ld(&bar[XB_XGEN(b.x)]) == gen, bar);
.LBB0_1012:
	s_lshl_b32 s4, s50, 8
	v_readlane_b32 s6, v254, 5
	v_readlane_b32 s7, v254, 6
	s_add_u32 s4, s6, s4
	s_addc_u32 s5, s7, 0
	v_mov_b32_e32 v2, 0x1000
	v_mov_b32_e32 v4, 1
	global_atomic_add v4, v2, v4, s[4:5] offset:1024 sc0
	v_cvt_f32_u32_e32 v2, v3
	v_sub_u32_e32 v5, 0, v3
	v_rcp_iflag_f32_e32 v2, v2
	s_nop 0
	v_mul_f32_e32 v2, 0x4f7ffffe, v2
	v_cvt_u32_f32_e32 v2, v2
	v_mul_lo_u32 v5, v5, v2
	v_mul_hi_u32 v5, v2, v5
	v_add_u32_e32 v2, v2, v5
	s_waitcnt vmcnt(0)
	v_mul_hi_u32 v2, v4, v2
	v_mul_lo_u32 v5, v2, v3
	v_sub_u32_e32 v5, v4, v5
	v_add_u32_e32 v6, 1, v2
	v_cmp_ge_u32_e32 vcc, v5, v3
	v_add_u32_e32 v4, 1, v4
	s_nop 0
	v_cndmask_b32_e32 v2, v2, v6, vcc
	v_sub_u32_e32 v6, v5, v3
	v_cndmask_b32_e32 v5, v5, v6, vcc
	v_add_u32_e32 v6, 1, v2
	v_cmp_ge_u32_e32 vcc, v5, v3
	s_nop 1
	v_cndmask_b32_e32 v2, v2, v6, vcc
	v_mul_lo_u32 v5, v3, v2
	v_add_u32_e32 v3, v5, v3
	v_cmp_ne_u32_e32 vcc, v4, v3
	s_and_saveexec_b64 s[6:7], vcc
	s_xor_b64 s[6:7], exec, s[6:7]
	s_cbranch_execz .LBB0_1026
	s_waitcnt lgkmcnt(0)
	s_add_u32 s14, s78, 0x83500
	s_addc_u32 s15, s79, 0
	v_mov_b32_e32 v1, 0
	global_load_dword v1, v1, s[14:15] sc1
	s_waitcnt vmcnt(0)
	v_cmp_gt_u32_e32 vcc, 9, v1
	s_and_saveexec_b64 s[8:9], vcc
	s_cbranch_execz .LBB0_1025
	s_add_u32 s10, s78, 0x80200
	s_addc_u32 s11, s79, 0
	s_mov_b32 s26, 1
	s_mov_b64 s[16:17], 0
	v_mov_b32_e32 v1, 0
	s_branch .LBB0_1016

; __device__ __forceinline__ unsigned xb_ld(unsigned* p)              { return __hip_atomic_load(p, __ATOMIC_RELAXED, __HIP_MEMORY_SCOPE_AGENT); }
; #define XB_SPIN(cond, bar) do { unsigned _sp = 0; while (cond) { __builtin_amdgcn_s_sleep(1); \
;     if ((++_sp & 255u) == 0u) { if (xb_ld(&(bar)[XB_TMO])) break; if (_sp > XB_SPIN_CAP) { atomicAdd(&(bar)[XB_TMO], 1u); break; } } } } while (0)
; __device__ __forceinline__ void xcd_barrier(const XcdBarrier& b) {
;     ...
;             XB_SPIN(xb_ld(&bar[XB_XGEN(b.x)]) == gen, bar);
.LBB0_1020:
	global_load_dword v3, v1, s[14:15] sc1
	s_add_i32 s26, s26, 1
	s_mov_b64 s[22:23], -1
	s_waitcnt vmcnt(0)
	v_cmp_le_u32_e32 vcc, 9, v3
	s_orn2_b64 s[20:21], vcc, exec
	s_branch .LBB0_1015
